# v079: v078 + MLA row-max chain: self-max canonicalisations of finite MFMA outputs dropped (2 VALU instead of 6 around the tree)
# baseline (speedup 1.0000x reference)
; #define MAX3F(a, b, c) __builtin_fmaxf(__builtin_fmaxf((a), (b)), (c))
; template <int DQK, int DKA, int DV> ...
;     ...
;             float mxa = MAX3F(p0[0], p0[1], p1[0]), mxb = MAX3F(p0[2], p0[3], p1[1]); mxa = MAX3F(mxa, p1[2], p1[3]);
; #pragma unroll
;             for (int i = 4; i < 16; i += 4) { mxa = MAX3F(mxa, p0[i], p0[i + 1]); mxb = MAX3F(mxb, p0[i + 2], p0[i + 3]); mxa = MAX3F(mxa, p1[i], p1[i + 1]); mxb = MAX3F(mxb, p1[i + 2], p1[i + 3]); }
;             float mx = fmaxf(mxa, mxb);
;             { auto rr = __builtin_amdgcn_permlane32_swap(__float_as_uint(mx), __float_as_uint(mx), false, false); mx = fmaxf(__uint_as_float(rr[0]), __uint_as_float(rr[1])); }
;             if (!NEGM) mx -= m;
;             if (t == 0) {
;                 m = mx;
;                 if (NEGM) {
; #pragma unroll
;                     for (int i = 0; i < 16; ++i) { p0[i] -= mx; p1[i] -= mx; }
; #pragma unroll
;                     for (int i = 0; i < 16; ++i) negm[i] = -m;
;                 }
;             } else if (__any(mx > RESC_THR)) {
;                 const float dl = fmaxf(mx, 0.f), alpha = __builtin_amdgcn_exp2f(-dl); m += dl;
;                 if (NEGM) {
; #pragma unroll
;                     for (int i = 0; i < 16; ++i) { p0[i] -= dl; p1[i] -= dl; }
; #pragma unroll
;                     for (int i = 0; i < 16; ++i) negm[i] = -m;
;                 }
;                 l *= alpha;
; #pragma unroll
;                 for (int v = 0; v < NV; ++v)
; #pragma unroll
;                     for (int i = 0; i < 16; ++i) o[v][i] *= alpha;
;             }
.LBB0_610:
	v_max_f32_e32 v148, v64, v65
	v_max3_f32 v149, v66, v67, v49
	v_max3_f32 v148, v148, v48, v50
	v_max3_f32 v148, v148, v51, v68
	v_max3_f32 v149, v149, v70, v71
	v_max3_f32 v148, v148, v69, v52
	v_max3_f32 v149, v149, v54, v55
	v_max3_f32 v148, v148, v53, v72
	v_max3_f32 v149, v149, v74, v75
	v_max3_f32 v148, v148, v73, v56
	v_max3_f32 v149, v149, v58, v59
	v_max3_f32 v148, v148, v57, v76
	v_max3_f32 v149, v149, v78, v79
	v_max3_f32 v148, v148, v77, v60
	v_max3_f32 v149, v149, v62, v63
	v_max3_f32 v148, v148, v61, v149
	v_mov_b32_e32 v149, v148
	s_nop 1
	v_permlane32_swap_b32_e32 v148, v149
	v_max_f32_e32 v148, v148, v149
	v_cmp_lt_f32_e32 vcc, s88, v148
	s_cbranch_vccz .LBB0_612
	v_max_f32_e32 v32, v148, v148
	v_max_f32_e32 v32, 0, v32
	v_exp_f32_e64 v148, -v32
	v_add_f32_e32 v199, v199, v32
	v_pk_add_f32 v[64:65], v[64:65], v[32:33] op_sel_hi:[1,0] neg_lo:[0,1] neg_hi:[0,1]
	v_pk_add_f32 v[48:49], v[48:49], v[32:33] op_sel_hi:[1,0] neg_lo:[0,1] neg_hi:[0,1]
	v_pk_add_f32 v[66:67], v[66:67], v[32:33] op_sel_hi:[1,0] neg_lo:[0,1] neg_hi:[0,1]
	v_pk_add_f32 v[50:51], v[50:51], v[32:33] op_sel_hi:[1,0] neg_lo:[0,1] neg_hi:[0,1]
	v_pk_add_f32 v[68:69], v[68:69], v[32:33] op_sel_hi:[1,0] neg_lo:[0,1] neg_hi:[0,1]
	v_pk_add_f32 v[52:53], v[52:53], v[32:33] op_sel_hi:[1,0] neg_lo:[0,1] neg_hi:[0,1]
	v_pk_add_f32 v[70:71], v[70:71], v[32:33] op_sel_hi:[1,0] neg_lo:[0,1] neg_hi:[0,1]
	v_pk_add_f32 v[54:55], v[54:55], v[32:33] op_sel_hi:[1,0] neg_lo:[0,1] neg_hi:[0,1]
	v_pk_add_f32 v[72:73], v[72:73], v[32:33] op_sel_hi:[1,0] neg_lo:[0,1] neg_hi:[0,1]
	v_pk_add_f32 v[56:57], v[56:57], v[32:33] op_sel_hi:[1,0] neg_lo:[0,1] neg_hi:[0,1]
	v_pk_add_f32 v[74:75], v[74:75], v[32:33] op_sel_hi:[1,0] neg_lo:[0,1] neg_hi:[0,1]
	v_pk_add_f32 v[58:59], v[58:59], v[32:33] op_sel_hi:[1,0] neg_lo:[0,1] neg_hi:[0,1]
	v_pk_add_f32 v[76:77], v[76:77], v[32:33] op_sel_hi:[1,0] neg_lo:[0,1] neg_hi:[0,1]
	v_pk_add_f32 v[60:61], v[60:61], v[32:33] op_sel_hi:[1,0] neg_lo:[0,1] neg_hi:[0,1]
	v_pk_add_f32 v[78:79], v[78:79], v[32:33] op_sel_hi:[1,0] neg_lo:[0,1] neg_hi:[0,1]
	v_pk_add_f32 v[62:63], v[62:63], v[32:33] op_sel_hi:[1,0] neg_lo:[0,1] neg_hi:[0,1]
	v_xor_b32_e32 v32, 0x80000000, v199
	v_mov_b32_e32 v33, v32
	v_mov_b32_e32 v34, v32
	v_mov_b32_e32 v35, v32
	v_mov_b32_e32 v36, v32
	v_mov_b32_e32 v37, v32
	v_mov_b32_e32 v38, v32
	v_mov_b32_e32 v39, v32
	v_mov_b32_e32 v40, v32
	v_mov_b32_e32 v41, v32
	v_mov_b32_e32 v42, v32
	v_mov_b32_e32 v43, v32
	v_mov_b32_e32 v44, v32
	v_mov_b32_e32 v45, v32
	v_mov_b32_e32 v46, v32
	v_mov_b32_e32 v47, v32
	v_pk_mul_f32 v[30:31], v[30:31], v[148:149] op_sel_hi:[1,0]
	v_pk_mul_f32 v[28:29], v[28:29], v[148:149] op_sel_hi:[1,0]
	v_pk_mul_f32 v[26:27], v[26:27], v[148:149] op_sel_hi:[1,0]
	v_pk_mul_f32 v[24:25], v[24:25], v[148:149] op_sel_hi:[1,0]
	v_pk_mul_f32 v[22:23], v[22:23], v[148:149] op_sel_hi:[1,0]
	v_pk_mul_f32 v[20:21], v[20:21], v[148:149] op_sel_hi:[1,0]
	v_pk_mul_f32 v[18:19], v[18:19], v[148:149] op_sel_hi:[1,0]
	v_pk_mul_f32 v[16:17], v[16:17], v[148:149] op_sel_hi:[1,0]
	v_pk_mul_f32 v[14:15], v[14:15], v[148:149] op_sel_hi:[1,0]
	v_pk_mul_f32 v[12:13], v[12:13], v[148:149] op_sel_hi:[1,0]
	v_pk_mul_f32 v[10:11], v[10:11], v[148:149] op_sel_hi:[1,0]
	v_pk_mul_f32 v[8:9], v[8:9], v[148:149] op_sel_hi:[1,0]
	v_pk_mul_f32 v[6:7], v[6:7], v[148:149] op_sel_hi:[1,0]
	v_pk_mul_f32 v[4:5], v[4:5], v[148:149] op_sel_hi:[1,0]
	v_pk_mul_f32 v[2:3], v[2:3], v[148:149] op_sel_hi:[1,0]
	v_pk_mul_f32 v[0:1], v[0:1], v[148:149] op_sel_hi:[1,0]
	v_mul_f32_e32 v185, v185, v148
